# HGRN2: waves 4-7 run matrix part before prep (complementary phases on each SIMD)
# speedup vs baseline: 1.0352x; 1.0127x over previous
.Lhg_dir_c:
	v_mov_b32_e32 v46, s32
	v_ashrrev_i32_e32 v47, 31, v46
	s_waitcnt vmcnt(0) lgkmcnt(0)
	s_barrier
	v_readlane_b32 s12, v252, 12
	s_cmp_ge_u32 s12, 4
	s_cbranch_scc0 .Lhc_norm_entry
	v_mov_b32_e32 v200, v44
	v_mov_b32_e32 v202, v42
	v_mov_b32_e32 v204, v40
	v_mov_b32_e32 v206, v38
	v_mov_b32_e32 v199, v45
	v_mov_b32_e32 v201, v43
	v_mov_b32_e32 v203, v41
	v_mov_b32_e32 v205, v39
	v_mov_b64_e32 v[152:153], v[36:37]
	s_branch .Lhc_alt_top
.Lhc_norm_entry:
	s_bitcmp1_b32 s61, 0
	s_cselect_b32 s62, 0x5800, 0
	s_cmp_gt_u32 s61, 14
	s_cbranch_scc1 .LBB0_944
	s_branch .LBB0_945

.LBB0_950:
	v_lshlrev_b32_e32 v0, 1, v135
	v_lshlrev_b32_e32 v1, 1, v154
	v_add3_u32 v2, s62, v0, v1
	v_add_u32_e32 v207, s62, v63
	v_lshl_add_u32 v227, v54, 1, v207
	v_add_u32_e32 v0, v2, v176
	ds_read_b128 v[36:39], v2 offset:4352
	ds_read_b128 v[40:43], v2
	ds_read_b128 v[208:211], v2 offset:4416
	ds_read_b128 v[184:187], v2 offset:64
	ds_read_b128 v[212:215], v2 offset:4480
	ds_read_b128 v[228:231], v2 offset:128
	ds_read_b128 v[232:235], v2 offset:4544
	ds_read_b128 v[236:239], v2 offset:192
	ds_read_b64 v[188:189], v227 offset:14848
	ds_read2_b64 v[240:243], v0 offset1:4
	ds_read2_b64 v[244:247], v0 offset0:8 offset1:12
	s_and_b64 s[12:13], s[54:55], s[52:53]
	v_mov_b32_e32 v190, v3
	v_mov_b32_e32 v191, v3
	s_waitcnt lgkmcnt(9)
	v_mfma_f32_16x16x32_bf16 v[36:39], v[36:39], v[40:43], 0
	s_waitcnt lgkmcnt(7)
	v_mfma_f32_16x16x32_bf16 v[36:39], v[208:211], v[184:187], v[36:39]
	s_waitcnt lgkmcnt(5)
	v_mfma_f32_16x16x32_bf16 v[36:39], v[212:215], v[228:231], v[36:39]
	s_waitcnt lgkmcnt(3)
	v_mfma_f32_16x16x32_bf16 v[36:39], v[232:235], v[236:239], v[36:39]
	ds_read2_b64 v[208:211], v0 offset0:16 offset1:20
	ds_read2_b64 v[212:215], v0 offset0:24 offset1:28
	v_cvt_pk_bf16_f32 v184, v4, v5
	v_cvt_pk_bf16_f32 v185, v6, v7
	v_cvt_pk_bf16_f32 v186, v8, v9
	v_cvt_pk_bf16_f32 v187, v10, v11
	v_mov_b32_e32 v2, v3
	s_nop 0
	v_cndmask_b32_e64 v192, v38, 0, s[12:13]
	s_and_b64 s[12:13], s[12:13], s[50:51]
	v_cndmask_b32_e64 v0, v37, 0, s[12:13]
	s_and_b64 s[12:13], s[12:13], s[48:49]
	v_cndmask_b32_e64 v36, v36, 0, s[12:13]
	v_cndmask_b32_e64 v1, v39, 0, s[54:55]
	v_cvt_pk_bf16_f32 v0, v36, v0
	v_cvt_pk_bf16_f32 v1, v192, v1
	s_nop 0
	s_waitcnt lgkmcnt(4)
	v_mfma_f32_16x16x32_bf16 v[36:39], v[0:3], v[188:191], 0
	v_cvt_pk_bf16_f32 v40, v12, v13
	v_cvt_pk_bf16_f32 v41, v14, v15
	v_cvt_pk_bf16_f32 v42, v16, v17
	v_cvt_pk_bf16_f32 v43, v18, v19
	v_cvt_pk_bf16_f32 v228, v20, v21
	v_cvt_pk_bf16_f32 v229, v22, v23
	v_cvt_pk_bf16_f32 v230, v24, v25
	v_cvt_pk_bf16_f32 v231, v26, v27
	v_cvt_pk_bf16_f32 v232, v28, v29
	v_cvt_pk_bf16_f32 v233, v30, v31
	v_cvt_pk_bf16_f32 v234, v32, v33
	v_cvt_pk_bf16_f32 v235, v34, v35
	s_waitcnt lgkmcnt(3)
	v_mfma_f32_16x16x32_bf16 v[36:39], v[240:243], v[184:187], v[36:39]
	s_waitcnt lgkmcnt(2)
	v_mfma_f32_16x16x32_bf16 v[36:39], v[244:247], v[40:43], v[36:39]
	s_waitcnt lgkmcnt(1)
	v_mfma_f32_16x16x32_bf16 v[36:39], v[208:211], v[228:231], v[36:39]
	s_waitcnt lgkmcnt(0)
	v_mfma_f32_16x16x32_bf16 v[36:39], v[212:215], v[232:235], v[36:39]
	v_add_u32_e32 v227, v207, v155
	v_lshl_add_u32 v216, v54, 2, s62
	v_add3_u32 v217, s62, v155, v156
	v_mov_b32_e32 v32, 0
	v_mov_b32_e32 v33, 0
	v_mov_b32_e32 v34, 0
	v_mov_b32_e32 v35, 0
	s_and_saveexec_b64 s[12:13], s[46:47]
	ds_read_b128 v[32:35], v227 offset:14848
	s_or_b64 exec, exec, s[12:13]
	ds_read_b128 v[240:243], v216 offset:20992
	ds_read_b128 v[184:187], v217 offset:8704
	ds_read_b128 v[244:247], v216 offset:21056
	ds_read_b128 v[40:43], v217 offset:9472
	ds_read_b128 v[208:211], v216 offset:21120
	ds_read_b128 v[228:231], v217 offset:10240
	ds_read_b128 v[212:215], v216 offset:21184
	ds_read_b128 v[232:235], v217 offset:11008
	v_cvt_pk_bf16_f32 v192, v36, s0
	global_store_short v197, v192, s[100:101]
	v_cvt_pk_bf16_f32 v193, v37, s0
	global_store_short v198, v193, s[100:101]
	v_cvt_pk_bf16_f32 v192, v38, s0
	global_store_short v248, v192, s[100:101]
	v_cvt_pk_bf16_f32 v193, v39, s0
	global_store_short v249, v193, s[100:101]
	s_waitcnt lgkmcnt(6)
	v_pk_mul_f32 v[6:7], v[6:7], v[242:243]
	v_pk_mul_f32 v[4:5], v[4:5], v[240:241]
	s_nop 1
	v_mfma_f32_16x16x32_bf16 v[4:7], v[184:187], v[32:35], v[4:7]
	ds_read_b128 v[240:243], v216 offset:21248
	ds_read_b128 v[184:187], v217 offset:11776
	s_waitcnt lgkmcnt(6)
	v_pk_mul_f32 v[10:11], v[10:11], v[246:247]
	v_pk_mul_f32 v[8:9], v[8:9], v[244:245]
	s_nop 1
	v_mfma_f32_16x16x32_bf16 v[8:11], v[40:43], v[32:35], v[8:11]
	ds_read_b128 v[244:247], v216 offset:21312
	ds_read_b128 v[40:43], v217 offset:12544
	s_waitcnt lgkmcnt(6)
	v_pk_mul_f32 v[14:15], v[14:15], v[210:211]
	v_pk_mul_f32 v[12:13], v[12:13], v[208:209]
	s_nop 1
	v_mfma_f32_16x16x32_bf16 v[12:15], v[228:231], v[32:35], v[12:15]
	ds_read_b128 v[208:211], v216 offset:21376
	ds_read_b128 v[228:231], v217 offset:13312
	s_waitcnt lgkmcnt(6)
	v_pk_mul_f32 v[18:19], v[18:19], v[214:215]
	v_pk_mul_f32 v[16:17], v[16:17], v[212:213]
	s_nop 1
	v_mfma_f32_16x16x32_bf16 v[16:19], v[232:235], v[32:35], v[16:19]
	ds_read_b128 v[212:215], v216 offset:21440
	ds_read_b128 v[232:235], v217 offset:14080
	s_waitcnt lgkmcnt(6)
	v_pk_mul_f32 v[22:23], v[22:23], v[242:243]
	v_pk_mul_f32 v[20:21], v[20:21], v[240:241]
	s_nop 1
	v_mfma_f32_16x16x32_bf16 v[20:23], v[184:187], v[32:35], v[20:23]
	s_waitcnt lgkmcnt(4)
	v_pk_mul_f32 v[26:27], v[26:27], v[246:247]
	v_pk_mul_f32 v[24:25], v[24:25], v[244:245]
	s_nop 1
	v_mfma_f32_16x16x32_bf16 v[24:27], v[40:43], v[32:35], v[24:27]
	s_waitcnt lgkmcnt(2)
	v_pk_mul_f32 v[30:31], v[30:31], v[210:211]
	v_pk_mul_f32 v[28:29], v[28:29], v[208:209]
	s_nop 1
	v_mfma_f32_16x16x32_bf16 v[28:31], v[228:231], v[32:35], v[28:31]
	s_waitcnt lgkmcnt(0)
	v_pk_mul_f32 v[214:215], v[150:151], v[214:215]
	v_pk_mul_f32 v[212:213], v[148:149], v[212:213]
	s_nop 1
	v_mfma_f32_16x16x32_bf16 v[32:35], v[232:235], v[32:35], v[212:215]
	v_add_u32_e32 v197, s32, v197
	v_add_u32_e32 v198, s32, v198
	v_add_u32_e32 v248, s32, v248
	v_add_u32_e32 v249, s32, v249
	v_lshl_add_u64 v[48:49], v[48:49], 0, v[46:47]
	s_add_i32 s60, s60, 16
	s_add_i32 s61, s61, 1
	s_cmpk_lg_i32 s60, 0x100
	s_barrier
	s_cbranch_scc1 .LBB0_943
	s_mov_b64 s[58:59], -1
	s_branch .LBB0_1005
.Lhc_alt_top:
	s_nop 2
	v_mov_b32_e32 v148, v32
	v_mov_b32_e32 v149, v33
	v_mov_b32_e32 v150, v34
	v_mov_b32_e32 v151, v35
	s_bitcmp1_b32 s61, 0
	s_cselect_b32 s62, 0x5800, 0
	v_lshlrev_b32_e32 v0, 1, v135
	v_lshlrev_b32_e32 v1, 1, v154
	v_add3_u32 v2, s62, v0, v1
	v_add_u32_e32 v207, s62, v63
	v_lshl_add_u32 v227, v54, 1, v207
	v_add_u32_e32 v0, v2, v176
	ds_read_b128 v[36:39], v2 offset:4352
	ds_read_b128 v[40:43], v2
	ds_read_b128 v[208:211], v2 offset:4416
	ds_read_b128 v[184:187], v2 offset:64
	ds_read_b128 v[212:215], v2 offset:4480
	ds_read_b128 v[228:231], v2 offset:128
	ds_read_b128 v[232:235], v2 offset:4544
	ds_read_b128 v[236:239], v2 offset:192
	ds_read_b64 v[188:189], v227 offset:14848
	ds_read2_b64 v[240:243], v0 offset1:4
	ds_read2_b64 v[244:247], v0 offset0:8 offset1:12
	s_and_b64 s[12:13], s[54:55], s[52:53]
	v_mov_b32_e32 v190, v3
	v_mov_b32_e32 v191, v3
	s_waitcnt lgkmcnt(9)
	v_mfma_f32_16x16x32_bf16 v[36:39], v[36:39], v[40:43], 0
	s_waitcnt lgkmcnt(7)
	v_mfma_f32_16x16x32_bf16 v[36:39], v[208:211], v[184:187], v[36:39]
	s_waitcnt lgkmcnt(5)
	v_mfma_f32_16x16x32_bf16 v[36:39], v[212:215], v[228:231], v[36:39]
	s_waitcnt lgkmcnt(3)
	v_mfma_f32_16x16x32_bf16 v[36:39], v[232:235], v[236:239], v[36:39]
	ds_read2_b64 v[208:211], v0 offset0:16 offset1:20
	ds_read2_b64 v[212:215], v0 offset0:24 offset1:28
	v_cvt_pk_bf16_f32 v184, v4, v5
	v_cvt_pk_bf16_f32 v185, v6, v7
	v_cvt_pk_bf16_f32 v186, v8, v9
	v_cvt_pk_bf16_f32 v187, v10, v11
	v_mov_b32_e32 v2, v3
	s_nop 0
	v_cndmask_b32_e64 v192, v38, 0, s[12:13]
	s_and_b64 s[12:13], s[12:13], s[50:51]
	v_cndmask_b32_e64 v0, v37, 0, s[12:13]
	s_and_b64 s[12:13], s[12:13], s[48:49]
	v_cndmask_b32_e64 v36, v36, 0, s[12:13]
	v_cndmask_b32_e64 v1, v39, 0, s[54:55]
	v_cvt_pk_bf16_f32 v0, v36, v0
	v_cvt_pk_bf16_f32 v1, v192, v1
	s_nop 0
	s_waitcnt lgkmcnt(4)
	v_mfma_f32_16x16x32_bf16 v[36:39], v[0:3], v[188:191], 0
	v_cvt_pk_bf16_f32 v40, v12, v13
	v_cvt_pk_bf16_f32 v41, v14, v15
	v_cvt_pk_bf16_f32 v42, v16, v17
	v_cvt_pk_bf16_f32 v43, v18, v19
	v_cvt_pk_bf16_f32 v228, v20, v21
	v_cvt_pk_bf16_f32 v229, v22, v23
	v_cvt_pk_bf16_f32 v230, v24, v25
	v_cvt_pk_bf16_f32 v231, v26, v27
	v_cvt_pk_bf16_f32 v232, v28, v29
	v_cvt_pk_bf16_f32 v233, v30, v31
	v_cvt_pk_bf16_f32 v234, v32, v33
	v_cvt_pk_bf16_f32 v235, v34, v35
	s_waitcnt lgkmcnt(3)
	v_mfma_f32_16x16x32_bf16 v[36:39], v[240:243], v[184:187], v[36:39]
	s_waitcnt lgkmcnt(2)
	v_mfma_f32_16x16x32_bf16 v[36:39], v[244:247], v[40:43], v[36:39]
	s_waitcnt lgkmcnt(1)
	v_mfma_f32_16x16x32_bf16 v[36:39], v[208:211], v[228:231], v[36:39]
	s_waitcnt lgkmcnt(0)
	v_mfma_f32_16x16x32_bf16 v[36:39], v[212:215], v[232:235], v[36:39]
	v_add_u32_e32 v227, v207, v155
	v_lshl_add_u32 v216, v54, 2, s62
	v_add3_u32 v217, s62, v155, v156
	v_mov_b32_e32 v32, 0
	v_mov_b32_e32 v33, 0
	v_mov_b32_e32 v34, 0
	v_mov_b32_e32 v35, 0
	s_and_saveexec_b64 s[12:13], s[46:47]
	ds_read_b128 v[32:35], v227 offset:14848
	s_or_b64 exec, exec, s[12:13]
	ds_read_b128 v[240:243], v216 offset:20992
	ds_read_b128 v[184:187], v217 offset:8704
	ds_read_b128 v[244:247], v216 offset:21056
	ds_read_b128 v[40:43], v217 offset:9472
	ds_read_b128 v[208:211], v216 offset:21120
	ds_read_b128 v[228:231], v217 offset:10240
	ds_read_b128 v[212:215], v216 offset:21184
	ds_read_b128 v[232:235], v217 offset:11008
	v_cvt_pk_bf16_f32 v192, v36, s0
	global_store_short v197, v192, s[100:101]
	v_cvt_pk_bf16_f32 v193, v37, s0
	global_store_short v198, v193, s[100:101]
	v_cvt_pk_bf16_f32 v192, v38, s0
	global_store_short v248, v192, s[100:101]
	v_cvt_pk_bf16_f32 v193, v39, s0
	global_store_short v249, v193, s[100:101]
	s_waitcnt lgkmcnt(6)
	v_pk_mul_f32 v[6:7], v[6:7], v[242:243]
	v_pk_mul_f32 v[4:5], v[4:5], v[240:241]
	s_nop 1
	v_mfma_f32_16x16x32_bf16 v[4:7], v[184:187], v[32:35], v[4:7]
	ds_read_b128 v[240:243], v216 offset:21248
	ds_read_b128 v[184:187], v217 offset:11776
	s_waitcnt lgkmcnt(6)
	v_pk_mul_f32 v[10:11], v[10:11], v[246:247]
	v_pk_mul_f32 v[8:9], v[8:9], v[244:245]
	s_nop 1
	v_mfma_f32_16x16x32_bf16 v[8:11], v[40:43], v[32:35], v[8:11]
	ds_read_b128 v[244:247], v216 offset:21312
	ds_read_b128 v[40:43], v217 offset:12544
	s_waitcnt lgkmcnt(6)
	v_pk_mul_f32 v[14:15], v[14:15], v[210:211]
	v_pk_mul_f32 v[12:13], v[12:13], v[208:209]
	s_nop 1
	v_mfma_f32_16x16x32_bf16 v[12:15], v[228:231], v[32:35], v[12:15]
	ds_read_b128 v[208:211], v216 offset:21376
	ds_read_b128 v[228:231], v217 offset:13312
	s_waitcnt lgkmcnt(6)
	v_pk_mul_f32 v[18:19], v[18:19], v[214:215]
	v_pk_mul_f32 v[16:17], v[16:17], v[212:213]
	s_nop 1
	v_mfma_f32_16x16x32_bf16 v[16:19], v[232:235], v[32:35], v[16:19]
	ds_read_b128 v[212:215], v216 offset:21440
	ds_read_b128 v[232:235], v217 offset:14080
	s_waitcnt lgkmcnt(6)
	v_pk_mul_f32 v[22:23], v[22:23], v[242:243]
	v_pk_mul_f32 v[20:21], v[20:21], v[240:241]
	s_nop 1
	v_mfma_f32_16x16x32_bf16 v[20:23], v[184:187], v[32:35], v[20:23]
	s_waitcnt lgkmcnt(4)
	v_pk_mul_f32 v[26:27], v[26:27], v[246:247]
	v_pk_mul_f32 v[24:25], v[24:25], v[244:245]
	s_nop 1
	v_mfma_f32_16x16x32_bf16 v[24:27], v[40:43], v[32:35], v[24:27]
	s_waitcnt lgkmcnt(2)
	v_pk_mul_f32 v[30:31], v[30:31], v[210:211]
	v_pk_mul_f32 v[28:29], v[28:29], v[208:209]
	s_nop 1
	v_mfma_f32_16x16x32_bf16 v[28:31], v[228:231], v[32:35], v[28:31]
	s_waitcnt lgkmcnt(0)
	v_pk_mul_f32 v[214:215], v[150:151], v[214:215]
	v_pk_mul_f32 v[212:213], v[148:149], v[212:213]
	s_nop 1
	v_mfma_f32_16x16x32_bf16 v[32:35], v[232:235], v[32:35], v[212:215]
	s_cmp_gt_u32 s61, 14
	s_cbranch_scc1 .Lhc_alt_tail
	s_waitcnt vmcnt(4)
	v_mov_b32_e32 v44, v200
	v_mov_b32_e32 v42, v202
	v_mov_b32_e32 v40, v204
	v_mov_b32_e32 v38, v206
	v_mov_b32_e32 v45, v199
	v_mov_b32_e32 v43, v201
	v_mov_b32_e32 v41, v203
	v_mov_b32_e32 v39, v205
	v_mov_b64_e32 v[36:37], v[152:153]
	s_cmpk_eq_i32 s60, 0xe0
	s_cbranch_scc1 .Lhc_alt_947
	global_load_ushort v199, v197, s[24:25]
	global_load_ushort v200, v197, s[98:99]
	global_load_ushort v201, v198, s[24:25]
	global_load_ushort v202, v198, s[98:99]
	global_load_ushort v203, v248, s[24:25]
	global_load_ushort v204, v248, s[98:99]
	global_load_ushort v205, v249, s[24:25]
	global_load_ushort v206, v249, s[98:99]
	global_load_dwordx2 v[152:153], v[48:49], off

.Lhc_alt_tail:
	s_waitcnt lgkmcnt(0)
	v_add_u32_e32 v197, s32, v197
	v_add_u32_e32 v198, s32, v198
	v_add_u32_e32 v248, s32, v248
	v_add_u32_e32 v249, s32, v249
	v_lshl_add_u64 v[48:49], v[48:49], 0, v[46:47]
	s_add_i32 s60, s60, 16
	s_add_i32 s61, s61, 1
	s_cmpk_lg_i32 s60, 0x100
	s_barrier
	s_cbranch_scc1 .Lhc_alt_top
	s_mov_b64 s[58:59], -1
	s_branch .LBB0_1005

.Lhg_dir_l:
	v_mov_b32_e32 v146, s32
	v_ashrrev_i32_e32 v147, 31, v146
	s_waitcnt vmcnt(0) lgkmcnt(0)
	v_mov_b32_e32 v157, v199
	v_mov_b32_e32 v159, v200
	v_mov_b32_e32 v161, v201
	v_mov_b32_e32 v163, v202
	v_mov_b32_e32 v166, v203
	v_mov_b32_e32 v167, v204
	v_mov_b32_e32 v168, v205
	v_mov_b32_e32 v169, v206
	v_mov_b64_e32 v[164:165], v[148:149]
	s_barrier
	v_readlane_b32 s14, v252, 12
	s_cmp_ge_u32 s14, 4
	s_cbranch_scc1 .Lhl_alt_top
	s_branch .LBB0_979

.LBB0_985:
	v_lshlrev_b32_e32 v0, 1, v135
	v_lshlrev_b32_e32 v1, 1, v154
	v_add3_u32 v2, s82, v0, v1
	v_add_u32_e32 v207, s82, v63
	v_lshl_add_u32 v227, v54, 1, v207
	v_add_u32_e32 v0, v2, v176
	ds_read_b128 v[36:39], v2 offset:4352
	ds_read_b128 v[40:43], v2
	ds_read_b128 v[208:211], v2 offset:4416
	ds_read_b128 v[184:187], v2 offset:64
	ds_read_b128 v[212:215], v2 offset:4480
	ds_read_b128 v[228:231], v2 offset:128
	ds_read_b128 v[232:235], v2 offset:4544
	ds_read_b128 v[236:239], v2 offset:192
	ds_read_b64 v[188:189], v227 offset:14848
	ds_read2_b64 v[240:243], v0 offset1:4
	ds_read2_b64 v[244:247], v0 offset0:8 offset1:12
	s_and_b64 s[14:15], s[54:55], s[52:53]
	v_mov_b32_e32 v190, v3
	v_mov_b32_e32 v191, v3
	s_waitcnt lgkmcnt(9)
	v_mfma_f32_16x16x32_bf16 v[36:39], v[36:39], v[40:43], 0
	s_waitcnt lgkmcnt(7)
	v_mfma_f32_16x16x32_bf16 v[36:39], v[208:211], v[184:187], v[36:39]
	s_waitcnt lgkmcnt(5)
	v_mfma_f32_16x16x32_bf16 v[36:39], v[212:215], v[228:231], v[36:39]
	s_waitcnt lgkmcnt(3)
	v_mfma_f32_16x16x32_bf16 v[36:39], v[232:235], v[236:239], v[36:39]
	ds_read2_b64 v[208:211], v0 offset0:16 offset1:20
	ds_read2_b64 v[212:215], v0 offset0:24 offset1:28
	v_cvt_pk_bf16_f32 v184, v4, v5
	v_cvt_pk_bf16_f32 v185, v6, v7
	v_cvt_pk_bf16_f32 v186, v8, v9
	v_cvt_pk_bf16_f32 v187, v10, v11
	v_mov_b32_e32 v2, v3
	s_nop 0
	v_cndmask_b32_e64 v192, v38, 0, s[14:15]
	s_and_b64 s[14:15], s[14:15], s[50:51]
	v_cndmask_b32_e64 v0, v37, 0, s[14:15]
	s_and_b64 s[14:15], s[14:15], s[48:49]
	v_cndmask_b32_e64 v36, v36, 0, s[14:15]
	v_cndmask_b32_e64 v1, v39, 0, s[54:55]
	v_cvt_pk_bf16_f32 v0, v36, v0
	v_cvt_pk_bf16_f32 v1, v192, v1
	s_nop 0
	s_waitcnt lgkmcnt(4)
	v_mfma_f32_16x16x32_bf16 v[36:39], v[0:3], v[188:191], 0
	v_cvt_pk_bf16_f32 v40, v12, v13
	v_cvt_pk_bf16_f32 v41, v14, v15
	v_cvt_pk_bf16_f32 v42, v16, v17
	v_cvt_pk_bf16_f32 v43, v18, v19
	v_cvt_pk_bf16_f32 v228, v20, v21
	v_cvt_pk_bf16_f32 v229, v22, v23
	v_cvt_pk_bf16_f32 v230, v24, v25
	v_cvt_pk_bf16_f32 v231, v26, v27
	v_cvt_pk_bf16_f32 v232, v28, v29
	v_cvt_pk_bf16_f32 v233, v30, v31
	v_cvt_pk_bf16_f32 v234, v32, v33
	v_cvt_pk_bf16_f32 v235, v34, v35
	s_waitcnt lgkmcnt(3)
	v_mfma_f32_16x16x32_bf16 v[36:39], v[240:243], v[184:187], v[36:39]
	s_waitcnt lgkmcnt(2)
	v_mfma_f32_16x16x32_bf16 v[36:39], v[244:247], v[40:43], v[36:39]
	s_waitcnt lgkmcnt(1)
	v_mfma_f32_16x16x32_bf16 v[36:39], v[208:211], v[228:231], v[36:39]
	s_waitcnt lgkmcnt(0)
	v_mfma_f32_16x16x32_bf16 v[36:39], v[212:215], v[232:235], v[36:39]
	v_add_u32_e32 v227, v207, v155
	v_lshl_add_u32 v216, v54, 2, s82
	v_add3_u32 v217, s82, v155, v156
	v_mov_b32_e32 v44, 0
	v_mov_b32_e32 v45, 0
	v_mov_b32_e32 v46, 0
	v_mov_b32_e32 v47, 0
	s_and_saveexec_b64 s[14:15], s[46:47]
	ds_read_b128 v[44:47], v227 offset:14848
	s_or_b64 exec, exec, s[14:15]
	ds_read_b128 v[240:243], v216 offset:20992
	ds_read_b128 v[184:187], v217 offset:8704
	ds_read_b128 v[244:247], v216 offset:21056
	ds_read_b128 v[40:43], v217 offset:9472
	ds_read_b128 v[208:211], v216 offset:21120
	ds_read_b128 v[228:231], v217 offset:10240
	ds_read_b128 v[212:215], v216 offset:21184
	ds_read_b128 v[232:235], v217 offset:11008
	v_cvt_pk_bf16_f32 v192, v36, s0
	global_store_short v197, v192, s[100:101]
	v_cvt_pk_bf16_f32 v193, v37, s0
	global_store_short v198, v193, s[100:101]
	v_cvt_pk_bf16_f32 v192, v38, s0
	global_store_short v178, v192, s[100:101]
	v_cvt_pk_bf16_f32 v193, v39, s0
	global_store_short v179, v193, s[100:101]
	s_waitcnt lgkmcnt(6)
	v_pk_mul_f32 v[6:7], v[6:7], v[242:243]
	v_pk_mul_f32 v[4:5], v[4:5], v[240:241]
	s_nop 1
	v_mfma_f32_16x16x32_bf16 v[4:7], v[184:187], v[44:47], v[4:7]
	ds_read_b128 v[240:243], v216 offset:21248
	ds_read_b128 v[184:187], v217 offset:11776
	s_waitcnt lgkmcnt(6)
	v_pk_mul_f32 v[10:11], v[10:11], v[246:247]
	v_pk_mul_f32 v[8:9], v[8:9], v[244:245]
	s_nop 1
	v_mfma_f32_16x16x32_bf16 v[8:11], v[40:43], v[44:47], v[8:11]
	ds_read_b128 v[244:247], v216 offset:21312
	ds_read_b128 v[40:43], v217 offset:12544
	s_waitcnt lgkmcnt(6)
	v_pk_mul_f32 v[14:15], v[14:15], v[210:211]
	v_pk_mul_f32 v[12:13], v[12:13], v[208:209]
	s_nop 1
	v_mfma_f32_16x16x32_bf16 v[12:15], v[228:231], v[44:47], v[12:15]
	ds_read_b128 v[208:211], v216 offset:21376
	ds_read_b128 v[228:231], v217 offset:13312
	s_waitcnt lgkmcnt(6)
	v_pk_mul_f32 v[18:19], v[18:19], v[214:215]
	v_pk_mul_f32 v[16:17], v[16:17], v[212:213]
	s_nop 1
	v_mfma_f32_16x16x32_bf16 v[16:19], v[232:235], v[44:47], v[16:19]
	ds_read_b128 v[212:215], v216 offset:21440
	ds_read_b128 v[232:235], v217 offset:14080
	s_waitcnt lgkmcnt(6)
	v_pk_mul_f32 v[22:23], v[22:23], v[242:243]
	v_pk_mul_f32 v[20:21], v[20:21], v[240:241]
	s_nop 1
	v_mfma_f32_16x16x32_bf16 v[20:23], v[184:187], v[44:47], v[20:23]
	s_waitcnt lgkmcnt(4)
	v_pk_mul_f32 v[26:27], v[26:27], v[246:247]
	v_pk_mul_f32 v[24:25], v[24:25], v[244:245]
	s_nop 1
	v_mfma_f32_16x16x32_bf16 v[24:27], v[40:43], v[44:47], v[24:27]
	s_waitcnt lgkmcnt(2)
	v_pk_mul_f32 v[30:31], v[30:31], v[210:211]
	v_pk_mul_f32 v[28:29], v[28:29], v[208:209]
	s_nop 1
	v_mfma_f32_16x16x32_bf16 v[28:31], v[228:231], v[44:47], v[28:31]
	s_waitcnt lgkmcnt(0)
	v_pk_mul_f32 v[34:35], v[34:35], v[214:215]
	v_pk_mul_f32 v[32:33], v[32:33], v[212:213]
	s_nop 1
	v_mfma_f32_16x16x32_bf16 v[32:35], v[232:235], v[44:47], v[32:35]
	v_add_u32_e32 v197, s32, v197
	v_add_u32_e32 v198, s32, v198
	v_add_u32_e32 v178, s32, v178
	v_add_u32_e32 v179, s32, v179
	v_lshl_add_u64 v[150:151], v[150:151], 0, v[146:147]
	s_add_i32 s81, s81, 1
	s_add_i32 s62, s62, 16
	s_add_i32 s14, s80, s81
	s_cmp_eq_u32 s14, 2
	s_barrier
	s_cbranch_scc1 .LBB0_1003
	s_branch .LBB0_979
.Lhl_alt_top:
	s_bitcmp1_b32 s81, 0
	s_cselect_b32 s82, 0x5800, 0
	v_lshlrev_b32_e32 v0, 1, v135
	v_lshlrev_b32_e32 v1, 1, v154
	v_add3_u32 v2, s82, v0, v1
	v_add_u32_e32 v207, s82, v63
	v_lshl_add_u32 v227, v54, 1, v207
	v_add_u32_e32 v0, v2, v176
	ds_read_b128 v[36:39], v2 offset:4352
	ds_read_b128 v[40:43], v2
	ds_read_b128 v[208:211], v2 offset:4416
	ds_read_b128 v[184:187], v2 offset:64
	ds_read_b128 v[212:215], v2 offset:4480
	ds_read_b128 v[228:231], v2 offset:128
	ds_read_b128 v[232:235], v2 offset:4544
	ds_read_b128 v[236:239], v2 offset:192
	ds_read_b64 v[188:189], v227 offset:14848
	ds_read2_b64 v[240:243], v0 offset1:4
	ds_read2_b64 v[244:247], v0 offset0:8 offset1:12
	s_and_b64 s[14:15], s[54:55], s[52:53]
	v_mov_b32_e32 v190, v3
	v_mov_b32_e32 v191, v3
	s_waitcnt lgkmcnt(9)
	v_mfma_f32_16x16x32_bf16 v[36:39], v[36:39], v[40:43], 0
	s_waitcnt lgkmcnt(7)
	v_mfma_f32_16x16x32_bf16 v[36:39], v[208:211], v[184:187], v[36:39]
	s_waitcnt lgkmcnt(5)
	v_mfma_f32_16x16x32_bf16 v[36:39], v[212:215], v[228:231], v[36:39]
	s_waitcnt lgkmcnt(3)
	v_mfma_f32_16x16x32_bf16 v[36:39], v[232:235], v[236:239], v[36:39]
	ds_read2_b64 v[208:211], v0 offset0:16 offset1:20
	ds_read2_b64 v[212:215], v0 offset0:24 offset1:28
	v_cvt_pk_bf16_f32 v184, v4, v5
	v_cvt_pk_bf16_f32 v185, v6, v7
	v_cvt_pk_bf16_f32 v186, v8, v9
	v_cvt_pk_bf16_f32 v187, v10, v11
	v_mov_b32_e32 v2, v3
	s_nop 0
	v_cndmask_b32_e64 v192, v38, 0, s[14:15]
	s_and_b64 s[14:15], s[14:15], s[50:51]
	v_cndmask_b32_e64 v0, v37, 0, s[14:15]
	s_and_b64 s[14:15], s[14:15], s[48:49]
	v_cndmask_b32_e64 v36, v36, 0, s[14:15]
	v_cndmask_b32_e64 v1, v39, 0, s[54:55]
	v_cvt_pk_bf16_f32 v0, v36, v0
	v_cvt_pk_bf16_f32 v1, v192, v1
	s_nop 0
	s_waitcnt lgkmcnt(4)
	v_mfma_f32_16x16x32_bf16 v[36:39], v[0:3], v[188:191], 0
	v_cvt_pk_bf16_f32 v40, v12, v13
	v_cvt_pk_bf16_f32 v41, v14, v15
	v_cvt_pk_bf16_f32 v42, v16, v17
	v_cvt_pk_bf16_f32 v43, v18, v19
	v_cvt_pk_bf16_f32 v228, v20, v21
	v_cvt_pk_bf16_f32 v229, v22, v23
	v_cvt_pk_bf16_f32 v230, v24, v25
	v_cvt_pk_bf16_f32 v231, v26, v27
	v_cvt_pk_bf16_f32 v232, v28, v29
	v_cvt_pk_bf16_f32 v233, v30, v31
	v_cvt_pk_bf16_f32 v234, v32, v33
	v_cvt_pk_bf16_f32 v235, v34, v35
	s_waitcnt lgkmcnt(3)
	v_mfma_f32_16x16x32_bf16 v[36:39], v[240:243], v[184:187], v[36:39]
	s_waitcnt lgkmcnt(2)
	v_mfma_f32_16x16x32_bf16 v[36:39], v[244:247], v[40:43], v[36:39]
	s_waitcnt lgkmcnt(1)
	v_mfma_f32_16x16x32_bf16 v[36:39], v[208:211], v[228:231], v[36:39]
	s_waitcnt lgkmcnt(0)
	v_mfma_f32_16x16x32_bf16 v[36:39], v[212:215], v[232:235], v[36:39]
	v_add_u32_e32 v227, v207, v155
	v_lshl_add_u32 v216, v54, 2, s82
	v_add3_u32 v217, s82, v155, v156
	v_mov_b32_e32 v44, 0
	v_mov_b32_e32 v45, 0
	v_mov_b32_e32 v46, 0
	v_mov_b32_e32 v47, 0
	s_and_saveexec_b64 s[14:15], s[46:47]
	ds_read_b128 v[44:47], v227 offset:14848
	s_or_b64 exec, exec, s[14:15]
	ds_read_b128 v[240:243], v216 offset:20992
	ds_read_b128 v[184:187], v217 offset:8704
	ds_read_b128 v[244:247], v216 offset:21056
	ds_read_b128 v[40:43], v217 offset:9472
	ds_read_b128 v[208:211], v216 offset:21120
	ds_read_b128 v[228:231], v217 offset:10240
	ds_read_b128 v[212:215], v216 offset:21184
	ds_read_b128 v[232:235], v217 offset:11008
	v_cvt_pk_bf16_f32 v192, v36, s0
	global_store_short v197, v192, s[100:101]
	v_cvt_pk_bf16_f32 v193, v37, s0
	global_store_short v198, v193, s[100:101]
	v_cvt_pk_bf16_f32 v192, v38, s0
	global_store_short v178, v192, s[100:101]
	v_cvt_pk_bf16_f32 v193, v39, s0
	global_store_short v179, v193, s[100:101]
	s_waitcnt lgkmcnt(6)
	v_pk_mul_f32 v[6:7], v[6:7], v[242:243]
	v_pk_mul_f32 v[4:5], v[4:5], v[240:241]
	s_nop 1
	v_mfma_f32_16x16x32_bf16 v[4:7], v[184:187], v[44:47], v[4:7]
	ds_read_b128 v[240:243], v216 offset:21248
	ds_read_b128 v[184:187], v217 offset:11776
	s_waitcnt lgkmcnt(6)
	v_pk_mul_f32 v[10:11], v[10:11], v[246:247]
	v_pk_mul_f32 v[8:9], v[8:9], v[244:245]
	s_nop 1
	v_mfma_f32_16x16x32_bf16 v[8:11], v[40:43], v[44:47], v[8:11]
	ds_read_b128 v[244:247], v216 offset:21312
	ds_read_b128 v[40:43], v217 offset:12544
	s_waitcnt lgkmcnt(6)
	v_pk_mul_f32 v[14:15], v[14:15], v[210:211]
	v_pk_mul_f32 v[12:13], v[12:13], v[208:209]
	s_nop 1
	v_mfma_f32_16x16x32_bf16 v[12:15], v[228:231], v[44:47], v[12:15]
	ds_read_b128 v[208:211], v216 offset:21376
	ds_read_b128 v[228:231], v217 offset:13312
	s_waitcnt lgkmcnt(6)
	v_pk_mul_f32 v[18:19], v[18:19], v[214:215]
	v_pk_mul_f32 v[16:17], v[16:17], v[212:213]
	s_nop 1
	v_mfma_f32_16x16x32_bf16 v[16:19], v[232:235], v[44:47], v[16:19]
	ds_read_b128 v[212:215], v216 offset:21440
	ds_read_b128 v[232:235], v217 offset:14080
	s_waitcnt lgkmcnt(6)
	v_pk_mul_f32 v[22:23], v[22:23], v[242:243]
	v_pk_mul_f32 v[20:21], v[20:21], v[240:241]
	s_nop 1
	v_mfma_f32_16x16x32_bf16 v[20:23], v[184:187], v[44:47], v[20:23]
	s_waitcnt lgkmcnt(4)
	v_pk_mul_f32 v[26:27], v[26:27], v[246:247]
	v_pk_mul_f32 v[24:25], v[24:25], v[244:245]
	s_nop 1
	v_mfma_f32_16x16x32_bf16 v[24:27], v[40:43], v[44:47], v[24:27]
	s_waitcnt lgkmcnt(2)
	v_pk_mul_f32 v[30:31], v[30:31], v[210:211]
	v_pk_mul_f32 v[28:29], v[28:29], v[208:209]
	s_nop 1
	v_mfma_f32_16x16x32_bf16 v[28:31], v[228:231], v[44:47], v[28:31]
	s_waitcnt lgkmcnt(0)
	v_pk_mul_f32 v[34:35], v[34:35], v[214:215]
	v_pk_mul_f32 v[32:33], v[32:33], v[212:213]
	s_nop 1
	v_mfma_f32_16x16x32_bf16 v[32:35], v[232:235], v[44:47], v[32:35]
	s_add_i32 s14, s81, -1
	s_cmp_ge_u32 s14, s61
	s_cbranch_scc1 .Lhl_alt_tail
	s_cmp_ge_u32 s81, s61
	s_waitcnt vmcnt(4)
	v_mov_b32_e32 v199, v157
	v_mov_b32_e32 v200, v159
	v_mov_b32_e32 v201, v161
	v_mov_b32_e32 v202, v163
	v_mov_b32_e32 v203, v166
	v_mov_b32_e32 v204, v167
	v_mov_b32_e32 v205, v168
	v_mov_b32_e32 v206, v169
	v_mov_b64_e32 v[148:149], v[164:165]
	s_cbranch_scc1 .Lhl_alt_982
	global_load_ushort v168, v197, s[12:13]
	global_load_ushort v169, v197, s[98:99]
	global_load_ushort v166, v198, s[12:13]
	global_load_ushort v167, v198, s[98:99]
	global_load_ushort v161, v178, s[12:13]
	global_load_ushort v163, v178, s[98:99]
	global_load_ushort v157, v179, s[12:13]
	global_load_ushort v159, v179, s[98:99]
	global_load_dwordx2 v[164:165], v[150:151], off

.Lhl_alt_tail:
	s_waitcnt lgkmcnt(0)
	v_add_u32_e32 v197, s32, v197
	v_add_u32_e32 v198, s32, v198
	v_add_u32_e32 v178, s32, v178
	v_add_u32_e32 v179, s32, v179
	v_lshl_add_u64 v[150:151], v[150:151], 0, v[146:147]
	s_add_i32 s81, s81, 1
	s_add_i32 s62, s62, 16
	s_add_i32 s14, s80, s81
	s_cmp_eq_u32 s14, 2
	s_barrier
	s_cbranch_scc1 .LBB0_1003
	s_branch .Lhl_alt_top
